# v1 + K-loop micro: s_setprio 1 hoisted above the pre-MFMA barrier, redundant post-barrier lgkmcnt(0) and mid-block setprio pair removed (P1 loop+peel, P4 loop)
# speedup vs baseline: 1.0438x; 1.0438x over previous
; #define PG8_STAGE(bufoff, gbase, voff) do { _Pragma("unroll") for (int _i = 0; _i < 2; ++_i) \
;         __builtin_amdgcn_global_load_lds((const unsigned*)((const char*)(gbase) + (voff)[_i]), (PG8_LAS unsigned*)(lds + (bufoff) + ldsw + _i * 8192), 16, 0, 0); } while (0)
; #define PG8_LDA(dst, b, h) do { _Pragma("unroll") for (int m = 0; m < 4; ++m) _Pragma("unroll") for (int k = 0; k < 2; ++k) dst[m][k] = *(const PG8_LAS bf16x8*)(lds + PG8_SA(b, h) + aoff + m * 2048 + k * 1024); } while (0)
; #define PG8_LDB(dst, b, h) do { _Pragma("unroll") for (int n = 0; n < 2; ++n) _Pragma("unroll") for (int k = 0; k < 2; ++k) dst[n][k] = *(const PG8_LAS bf16x8*)(lds + PG8_SB(b, h) + boff + n * 2048 + k * 1024); } while (0)
; #define PG8_MMA(ai, bj, At, Bt) do { __builtin_amdgcn_s_setprio(1); _Pragma("unroll") for (int m = 0; m < 4; ++m) _Pragma("unroll") for (int n = 0; n < 2; ++n) _Pragma("unroll") for (int k = 0; k < 2; ++k) \
;         acc[ai][bj][m][n] = __builtin_amdgcn_mfma_f32_16x16x32_bf16(Bt[n][k], At[m][k], acc[ai][bj][m][n], 0, 0, 0); __builtin_amdgcn_s_setprio(0); } while (0)
; #define PG8_WAIT_V(n) asm volatile("s_waitcnt vmcnt(" #n ")" ::: "memory")
; #define PG8_WAIT_L(n) asm volatile("s_waitcnt lgkmcnt(" #n ")" ::: "memory")
; #define PG8_BAR __builtin_amdgcn_s_barrier()
; #define PG8_SCHED __builtin_amdgcn_sched_barrier(0)
; template <class Epi, class Sched, bool ALIGN_EPI = false, bool SP2 = false>
; __device__ __forceinline__ void gemm_phase(PG8_LAS unsigned char* lds, const Gemm g, const Sched& S, const Epi& E) {
;     ...
;             PG8_LDB(B0, 0, 0); PG8_LDB(B1, 0, 1); PG8_SCHED; PG8_LDA(At, 0, 0); PG8_STAGE(PG8_SA(1, 1), a1 + hstep, voffA);
;             PG8_WAIT_V(8); PG8_WAIT_L(0); PG8_BAR; PG8_MMA(0, 0, At, B0); PG8_MMA(0, 1, At, B1); PG8_BAR; PG8_SCHED;
;             PG8_LDA(At, 0, 1); PG8_STAGE(PG8_SB(0, 0), b2, voffB); PG8_STAGE(PG8_SB(0, 1), b2 + hstep, voffB); PG8_STAGE(PG8_SA(0, 0), a2, voffA);
;             PG8_WAIT_V(8); PG8_WAIT_L(0); PG8_BAR; PG8_MMA(1, 0, At, B0); PG8_MMA(1, 1, At, B1); PG8_BAR; PG8_SCHED;
.LBB0_162:
	ds_read_b128 v[130:133], v183
	ds_read_b128 v[134:137], v183 offset:1024
	ds_read_b128 v[138:141], v183 offset:2048
	ds_read_b128 v[142:145], v183 offset:3072
	ds_read_b128 v[172:175], v184
	ds_read_b128 v[176:179], v184 offset:1024
	ds_read_b128 v[192:195], v184 offset:2048
	ds_read_b128 v[196:199], v184 offset:3072
	s_add_u32 s50, s48, 0xfffc0080
	s_addc_u32 s51, s49, -1
	s_cmp_eq_u32 s93, 12
	s_cselect_b32 s65, s5, s51
	s_cselect_b32 s64, s34, s50
	s_cselect_b32 s51, s27, s92
	s_cselect_b32 s50, s35, s41
	v_lshl_add_u64 v[232:233], s[48:49], 0, v[164:165]
	s_add_i32 m0, s47, 0xc000
	ds_read_b128 v[200:203], v185
	ds_read_b128 v[204:207], v185 offset:1024
	ds_read_b128 v[208:211], v185 offset:2048
	ds_read_b128 v[212:215], v185 offset:3072
	ds_read_b128 v[216:219], v185 offset:4096
	ds_read_b128 v[220:223], v185 offset:5120
	ds_read_b128 v[224:227], v185 offset:6144
	ds_read_b128 v[228:231], v185 offset:7168
	global_load_lds_dwordx4 v[232:233], off
	v_lshl_add_u64 v[232:233], s[48:49], 0, v[166:167]
	s_add_i32 m0, s47, 0xe000
	s_nop 0
	global_load_lds_dwordx4 v[232:233], off
	s_waitcnt vmcnt(8)
	s_waitcnt lgkmcnt(0)
	s_setprio 1
	s_barrier
	v_mfma_f32_16x16x32_bf16 v[126:129], v[130:133], v[200:203], v[126:129]
	v_mfma_f32_16x16x32_bf16 v[122:125], v[138:141], v[200:203], v[122:125]
	v_mfma_f32_16x16x32_bf16 v[110:113], v[130:133], v[208:211], v[110:113]
	v_mfma_f32_16x16x32_bf16 v[106:109], v[138:141], v[208:211], v[106:109]
	v_mfma_f32_16x16x32_bf16 v[94:97], v[130:133], v[216:219], v[94:97]
	v_mfma_f32_16x16x32_bf16 v[90:93], v[138:141], v[216:219], v[90:93]
	v_mfma_f32_16x16x32_bf16 v[78:81], v[130:133], v[224:227], v[78:81]
	v_mfma_f32_16x16x32_bf16 v[74:77], v[138:141], v[224:227], v[74:77]
	v_mfma_f32_16x16x32_bf16 v[126:129], v[134:137], v[204:207], v[126:129]
	v_mfma_f32_16x16x32_bf16 v[122:125], v[142:145], v[204:207], v[122:125]
	v_mfma_f32_16x16x32_bf16 v[110:113], v[134:137], v[212:215], v[110:113]
	v_mfma_f32_16x16x32_bf16 v[106:109], v[142:145], v[212:215], v[106:109]
	v_mfma_f32_16x16x32_bf16 v[94:97], v[134:137], v[220:223], v[94:97]
	v_mfma_f32_16x16x32_bf16 v[90:93], v[142:145], v[220:223], v[90:93]
	v_mfma_f32_16x16x32_bf16 v[78:81], v[134:137], v[228:231], v[78:81]
	v_mfma_f32_16x16x32_bf16 v[74:77], v[142:145], v[228:231], v[74:77]
	v_mfma_f32_16x16x32_bf16 v[118:121], v[172:175], v[200:203], v[118:121]
	v_mfma_f32_16x16x32_bf16 v[114:117], v[192:195], v[200:203], v[114:117]
	v_mfma_f32_16x16x32_bf16 v[102:105], v[172:175], v[208:211], v[102:105]
	v_mfma_f32_16x16x32_bf16 v[98:101], v[192:195], v[208:211], v[98:101]
	v_mfma_f32_16x16x32_bf16 v[86:89], v[172:175], v[216:219], v[86:89]
	v_mfma_f32_16x16x32_bf16 v[82:85], v[192:195], v[216:219], v[82:85]
	v_mfma_f32_16x16x32_bf16 v[70:73], v[172:175], v[224:227], v[70:73]
	v_mfma_f32_16x16x32_bf16 v[66:69], v[192:195], v[224:227], v[66:69]
	v_mfma_f32_16x16x32_bf16 v[118:121], v[176:179], v[204:207], v[118:121]
	v_mfma_f32_16x16x32_bf16 v[114:117], v[196:199], v[204:207], v[114:117]
	v_mfma_f32_16x16x32_bf16 v[102:105], v[176:179], v[212:215], v[102:105]
	v_mfma_f32_16x16x32_bf16 v[98:101], v[196:199], v[212:215], v[98:101]
	v_mfma_f32_16x16x32_bf16 v[86:89], v[176:179], v[220:223], v[86:89]
	v_mfma_f32_16x16x32_bf16 v[82:85], v[196:199], v[220:223], v[82:85]
	v_mfma_f32_16x16x32_bf16 v[70:73], v[176:179], v[228:231], v[70:73]
	v_mfma_f32_16x16x32_bf16 v[66:69], v[196:199], v[228:231], v[66:69]
	s_setprio 0
	s_barrier
	s_add_i32 s94, s85, s72
	v_lshl_add_u64 v[232:233], s[50:51], 0, v[148:149]
	s_mov_b32 m0, s94
	ds_read_b128 v[200:203], v185 offset:16384
	ds_read_b128 v[204:207], v185 offset:17408
	ds_read_b128 v[208:211], v185 offset:18432
	ds_read_b128 v[212:215], v185 offset:19456
	ds_read_b128 v[216:219], v185 offset:20480
	ds_read_b128 v[220:223], v185 offset:21504
	ds_read_b128 v[224:227], v185 offset:22528
	ds_read_b128 v[228:231], v185 offset:23552
	global_load_lds_dwordx4 v[232:233], off
	s_add_i32 m0, s94, 0x2000
	s_add_u32 s94, s50, 0x40000
	v_lshl_add_u64 v[234:235], s[50:51], 0, v[152:153]
	s_addc_u32 s95, s51, 0
	s_add_i32 s96, s86, s72
	global_load_lds_dwordx4 v[234:235], off
	v_lshl_add_u64 v[236:237], s[94:95], 0, v[148:149]
	s_mov_b32 m0, s96
	v_lshl_add_u64 v[238:239], s[64:65], 0, v[150:151]
	global_load_lds_dwordx4 v[236:237], off
	v_lshl_add_u64 v[236:237], s[94:95], 0, v[152:153]
	s_add_i32 m0, s96, 0x2000
	s_nop 0
	global_load_lds_dwordx4 v[236:237], off
	v_lshl_add_u64 v[236:237], s[64:65], 0, v[146:147]
	s_mov_b32 m0, s47
	s_nop 0
	global_load_lds_dwordx4 v[236:237], off
	s_mov_b32 m0, s73
	s_nop 0
	global_load_lds_dwordx4 v[238:239], off
	s_waitcnt vmcnt(8)
	s_waitcnt lgkmcnt(0)
	s_setprio 1
	s_barrier
; #define PG8_STAGE(bufoff, gbase, voff) do { _Pragma("unroll") for (int _i = 0; _i < 2; ++_i) \
;         __builtin_amdgcn_global_load_lds((const unsigned*)((const char*)(gbase) + (voff)[_i]), (PG8_LAS unsigned*)(lds + (bufoff) + ldsw + _i * 8192), 16, 0, 0); } while (0)
; #define PG8_LDA(dst, b, h) do { _Pragma("unroll") for (int m = 0; m < 4; ++m) _Pragma("unroll") for (int k = 0; k < 2; ++k) dst[m][k] = *(const PG8_LAS bf16x8*)(lds + PG8_SA(b, h) + aoff + m * 2048 + k * 1024); } while (0)
; #define PG8_LDB(dst, b, h) do { _Pragma("unroll") for (int n = 0; n < 2; ++n) _Pragma("unroll") for (int k = 0; k < 2; ++k) dst[n][k] = *(const PG8_LAS bf16x8*)(lds + PG8_SB(b, h) + boff + n * 2048 + k * 1024); } while (0)
; #define PG8_MMA(ai, bj, At, Bt) do { __builtin_amdgcn_s_setprio(1); _Pragma("unroll") for (int m = 0; m < 4; ++m) _Pragma("unroll") for (int n = 0; n < 2; ++n) _Pragma("unroll") for (int k = 0; k < 2; ++k) \
;         acc[ai][bj][m][n] = __builtin_amdgcn_mfma_f32_16x16x32_bf16(Bt[n][k], At[m][k], acc[ai][bj][m][n], 0, 0, 0); __builtin_amdgcn_s_setprio(0); } while (0)
; #define PG8_WAIT_V(n) asm volatile("s_waitcnt vmcnt(" #n ")" ::: "memory")
; #define PG8_WAIT_L(n) asm volatile("s_waitcnt lgkmcnt(" #n ")" ::: "memory")
; #define PG8_BAR __builtin_amdgcn_s_barrier()
; #define PG8_SCHED __builtin_amdgcn_sched_barrier(0)
; template <class Epi, class Sched, bool ALIGN_EPI = false, bool SP2 = false>
; __device__ __forceinline__ void gemm_phase(PG8_LAS unsigned char* lds, const Gemm g, const Sched& S, const Epi& E) {
;     ...
;             PG8_WAIT_V(8); PG8_WAIT_L(0); PG8_BAR; PG8_MMA(1, 0, At, B0); PG8_MMA(1, 1, At, B1); PG8_BAR; PG8_SCHED;
;             PG8_LDB(B0, 1, 0); PG8_LDB(B1, 1, 1); PG8_SCHED; PG8_LDA(At, 1, 0); PG8_STAGE(PG8_SA(0, 1), a2 + hstep, voffA);
;             PG8_WAIT_V(8); PG8_WAIT_L(0); PG8_BAR; PG8_MMA(0, 0, At, B0); PG8_MMA(0, 1, At, B1); PG8_BAR; PG8_SCHED;
	v_mfma_f32_16x16x32_bf16 v[62:65], v[130:133], v[200:203], v[62:65]
	v_mfma_f32_16x16x32_bf16 v[58:61], v[138:141], v[200:203], v[58:61]
	v_mfma_f32_16x16x32_bf16 v[46:49], v[130:133], v[208:211], v[46:49]
	v_mfma_f32_16x16x32_bf16 v[42:45], v[138:141], v[208:211], v[42:45]
	v_mfma_f32_16x16x32_bf16 v[30:33], v[130:133], v[216:219], v[30:33]
	v_mfma_f32_16x16x32_bf16 v[26:29], v[138:141], v[216:219], v[26:29]
	v_mfma_f32_16x16x32_bf16 v[14:17], v[130:133], v[224:227], v[14:17]
	v_mfma_f32_16x16x32_bf16 v[10:13], v[138:141], v[224:227], v[10:13]
	v_mfma_f32_16x16x32_bf16 v[62:65], v[134:137], v[204:207], v[62:65]
	v_mfma_f32_16x16x32_bf16 v[58:61], v[142:145], v[204:207], v[58:61]
	v_mfma_f32_16x16x32_bf16 v[46:49], v[134:137], v[212:215], v[46:49]
	v_mfma_f32_16x16x32_bf16 v[42:45], v[142:145], v[212:215], v[42:45]
	v_mfma_f32_16x16x32_bf16 v[30:33], v[134:137], v[220:223], v[30:33]
	v_mfma_f32_16x16x32_bf16 v[26:29], v[142:145], v[220:223], v[26:29]
	v_mfma_f32_16x16x32_bf16 v[14:17], v[134:137], v[228:231], v[14:17]
	v_mfma_f32_16x16x32_bf16 v[10:13], v[142:145], v[228:231], v[10:13]
	v_mfma_f32_16x16x32_bf16 v[54:57], v[172:175], v[200:203], v[54:57]
	v_mfma_f32_16x16x32_bf16 v[50:53], v[192:195], v[200:203], v[50:53]
	v_mfma_f32_16x16x32_bf16 v[38:41], v[172:175], v[208:211], v[38:41]
	v_mfma_f32_16x16x32_bf16 v[34:37], v[192:195], v[208:211], v[34:37]
	v_mfma_f32_16x16x32_bf16 v[22:25], v[172:175], v[216:219], v[22:25]
	v_mfma_f32_16x16x32_bf16 v[18:21], v[192:195], v[216:219], v[18:21]
	v_mfma_f32_16x16x32_bf16 v[6:9], v[172:175], v[224:227], v[6:9]
	v_mfma_f32_16x16x32_bf16 v[2:5], v[192:195], v[224:227], v[2:5]
	v_mfma_f32_16x16x32_bf16 v[54:57], v[176:179], v[204:207], v[54:57]
	v_mfma_f32_16x16x32_bf16 v[50:53], v[196:199], v[204:207], v[50:53]
	v_mfma_f32_16x16x32_bf16 v[38:41], v[176:179], v[212:215], v[38:41]
	v_mfma_f32_16x16x32_bf16 v[34:37], v[196:199], v[212:215], v[34:37]
	v_mfma_f32_16x16x32_bf16 v[22:25], v[176:179], v[220:223], v[22:25]
	v_mfma_f32_16x16x32_bf16 v[18:21], v[196:199], v[220:223], v[18:21]
	v_mfma_f32_16x16x32_bf16 v[6:9], v[176:179], v[228:231], v[6:9]
	v_mfma_f32_16x16x32_bf16 v[2:5], v[196:199], v[228:231], v[2:5]
	s_setprio 0
	s_barrier
	s_add_i32 s94, 0, 0x18000
	s_add_i32 s95, 0, 0x1c000
	v_add_u32_e32 v142, s94, v181
	v_add_u32_e32 v154, s95, v181
	ds_read_b128 v[130:133], v142
	ds_read_b128 v[134:137], v142 offset:1024
	ds_read_b128 v[138:141], v142 offset:2048
	ds_read_b128 v[142:145], v142 offset:3072
	ds_read_b128 v[172:175], v154
	ds_read_b128 v[176:179], v154 offset:1024
	ds_read_b128 v[192:195], v154 offset:2048
	ds_read_b128 v[196:199], v154 offset:3072
	s_add_u32 s64, s64, 0x40000
	s_addc_u32 s65, s65, 0
	s_mov_b32 m0, s74
	v_lshl_add_u64 v[240:241], s[64:65], 0, v[146:147]
	ds_read_b128 v[200:203], v185 offset:32768
	ds_read_b128 v[204:207], v185 offset:33792
	ds_read_b128 v[208:211], v185 offset:34816
	ds_read_b128 v[212:215], v185 offset:35840
	ds_read_b128 v[216:219], v185 offset:36864
	ds_read_b128 v[220:223], v185 offset:37888
	ds_read_b128 v[224:227], v185 offset:38912
	ds_read_b128 v[228:231], v185 offset:39936
	global_load_lds_dwordx4 v[240:241], off
	v_lshl_add_u64 v[240:241], s[64:65], 0, v[150:151]
	s_mov_b32 m0, s75
	s_nop 0
	global_load_lds_dwordx4 v[240:241], off
	s_waitcnt vmcnt(8)
	s_waitcnt lgkmcnt(0)
	s_setprio 1
	s_barrier
	v_mfma_f32_16x16x32_bf16 v[126:129], v[130:133], v[200:203], v[126:129]
	v_mfma_f32_16x16x32_bf16 v[122:125], v[138:141], v[200:203], v[122:125]
	v_mfma_f32_16x16x32_bf16 v[110:113], v[130:133], v[208:211], v[110:113]
	v_mfma_f32_16x16x32_bf16 v[106:109], v[138:141], v[208:211], v[106:109]
	v_mfma_f32_16x16x32_bf16 v[94:97], v[130:133], v[216:219], v[94:97]
	v_mfma_f32_16x16x32_bf16 v[90:93], v[138:141], v[216:219], v[90:93]
	v_mfma_f32_16x16x32_bf16 v[78:81], v[130:133], v[224:227], v[78:81]
	v_mfma_f32_16x16x32_bf16 v[74:77], v[138:141], v[224:227], v[74:77]
	v_mfma_f32_16x16x32_bf16 v[126:129], v[134:137], v[204:207], v[126:129]
	v_mfma_f32_16x16x32_bf16 v[122:125], v[142:145], v[204:207], v[122:125]
	v_mfma_f32_16x16x32_bf16 v[110:113], v[134:137], v[212:215], v[110:113]
	v_mfma_f32_16x16x32_bf16 v[106:109], v[142:145], v[212:215], v[106:109]
	v_mfma_f32_16x16x32_bf16 v[94:97], v[134:137], v[220:223], v[94:97]
	v_mfma_f32_16x16x32_bf16 v[90:93], v[142:145], v[220:223], v[90:93]
	v_mfma_f32_16x16x32_bf16 v[78:81], v[134:137], v[228:231], v[78:81]
	v_mfma_f32_16x16x32_bf16 v[74:77], v[142:145], v[228:231], v[74:77]
	v_mfma_f32_16x16x32_bf16 v[118:121], v[172:175], v[200:203], v[118:121]
	v_mfma_f32_16x16x32_bf16 v[114:117], v[192:195], v[200:203], v[114:117]
	v_mfma_f32_16x16x32_bf16 v[102:105], v[172:175], v[208:211], v[102:105]
	v_mfma_f32_16x16x32_bf16 v[98:101], v[192:195], v[208:211], v[98:101]
	v_mfma_f32_16x16x32_bf16 v[86:89], v[172:175], v[216:219], v[86:89]
	v_mfma_f32_16x16x32_bf16 v[82:85], v[192:195], v[216:219], v[82:85]
	v_mfma_f32_16x16x32_bf16 v[70:73], v[172:175], v[224:227], v[70:73]
	v_mfma_f32_16x16x32_bf16 v[66:69], v[192:195], v[224:227], v[66:69]
	v_mfma_f32_16x16x32_bf16 v[118:121], v[176:179], v[204:207], v[118:121]
	v_mfma_f32_16x16x32_bf16 v[114:117], v[196:199], v[204:207], v[114:117]
	v_mfma_f32_16x16x32_bf16 v[102:105], v[176:179], v[212:215], v[102:105]
	v_mfma_f32_16x16x32_bf16 v[98:101], v[196:199], v[212:215], v[98:101]
	v_mfma_f32_16x16x32_bf16 v[86:89], v[176:179], v[220:223], v[86:89]
	v_mfma_f32_16x16x32_bf16 v[82:85], v[196:199], v[220:223], v[82:85]
	v_mfma_f32_16x16x32_bf16 v[70:73], v[176:179], v[228:231], v[70:73]
	v_mfma_f32_16x16x32_bf16 v[66:69], v[196:199], v[228:231], v[66:69]
	s_setprio 0
	s_barrier
; #define PG8_STAGE(bufoff, gbase, voff) do { _Pragma("unroll") for (int _i = 0; _i < 2; ++_i) \
;         __builtin_amdgcn_global_load_lds((const unsigned*)((const char*)(gbase) + (voff)[_i]), (PG8_LAS unsigned*)(lds + (bufoff) + ldsw + _i * 8192), 16, 0, 0); } while (0)
; #define PG8_LDA(dst, b, h) do { _Pragma("unroll") for (int m = 0; m < 4; ++m) _Pragma("unroll") for (int k = 0; k < 2; ++k) dst[m][k] = *(const PG8_LAS bf16x8*)(lds + PG8_SA(b, h) + aoff + m * 2048 + k * 1024); } while (0)
; #define PG8_MMA(ai, bj, At, Bt) do { __builtin_amdgcn_s_setprio(1); _Pragma("unroll") for (int m = 0; m < 4; ++m) _Pragma("unroll") for (int n = 0; n < 2; ++n) _Pragma("unroll") for (int k = 0; k < 2; ++k) \
;         acc[ai][bj][m][n] = __builtin_amdgcn_mfma_f32_16x16x32_bf16(Bt[n][k], At[m][k], acc[ai][bj][m][n], 0, 0, 0); __builtin_amdgcn_s_setprio(0); } while (0)
; #define PG8_WAIT_V(n) asm volatile("s_waitcnt vmcnt(" #n ")" ::: "memory")
; #define PG8_WAIT_L(n) asm volatile("s_waitcnt lgkmcnt(" #n ")" ::: "memory")
; #define PG8_BAR __builtin_amdgcn_s_barrier()
; #define PG8_SCHED __builtin_amdgcn_sched_barrier(0)
; template <class Epi, class Sched, bool ALIGN_EPI = false, bool SP2 = false>
; __device__ __forceinline__ void gemm_phase(PG8_LAS unsigned char* lds, const Gemm g, const Sched& S, const Epi& E) {
;     ...
;         for (int t = 0; t < nt; t += 2) {
;             const bool last = (t == nt - 2);
;             const char* a1 = cA + (size_t)(t + 1) * kstep;
;             const char* a2 = last ? nA : cA + (size_t)(t + 2) * kstep; const char* b2 = last ? nB : cB + (size_t)(t + 2) * kstep;
;             const char* a3 = a2 + kstep; const char* b3 = b2 + kstep;
;     ...
;             PG8_LDA(At, 1, 1); PG8_STAGE(PG8_SB(1, 0), b3, voffB); PG8_STAGE(PG8_SB(1, 1), b3 + hstep, voffB); PG8_STAGE(PG8_SA(1, 0), a3, voffA);
;             PG8_WAIT_V(8); PG8_WAIT_L(0); PG8_BAR; PG8_MMA(1, 0, At, B0); PG8_MMA(1, 1, At, B1); PG8_BAR; PG8_SCHED;
	s_add_i32 s64, s94, s72
	v_lshl_add_u64 v[232:233], v[232:233], 0, s[12:13]
	s_mov_b32 m0, s64
	ds_read_b128 v[200:203], v185 offset:49152
	ds_read_b128 v[204:207], v185 offset:50176
	ds_read_b128 v[208:211], v185 offset:51200
	ds_read_b128 v[212:215], v185 offset:52224
	ds_read_b128 v[216:219], v185 offset:53248
	ds_read_b128 v[220:223], v185 offset:54272
	ds_read_b128 v[224:227], v185 offset:55296
	ds_read_b128 v[228:231], v185 offset:56320
	global_load_lds_dwordx4 v[232:233], off
	s_add_i32 m0, s64, 0x2000
	s_add_u32 s50, s50, 0x40080
	v_lshl_add_u64 v[232:233], v[234:235], 0, s[12:13]
	s_addc_u32 s51, s51, 0
	s_add_i32 s64, s95, s72
	global_load_lds_dwordx4 v[232:233], off
	v_lshl_add_u64 v[232:233], s[50:51], 0, v[148:149]
	s_mov_b32 m0, s64
	s_nop 0
	global_load_lds_dwordx4 v[232:233], off
	v_lshl_add_u64 v[232:233], s[50:51], 0, v[152:153]
	s_add_i32 m0, s64, 0x2000
	s_nop 0
	global_load_lds_dwordx4 v[232:233], off
	v_lshl_add_u64 v[232:233], v[236:237], 0, s[12:13]
	s_mov_b32 m0, s82
	s_nop 0
	global_load_lds_dwordx4 v[232:233], off
	v_lshl_add_u64 v[232:233], v[238:239], 0, s[12:13]
	s_mov_b32 m0, s83
	s_nop 0
	global_load_lds_dwordx4 v[232:233], off
	s_waitcnt vmcnt(8)
	s_waitcnt lgkmcnt(0)
	s_setprio 1
	s_barrier
	v_mfma_f32_16x16x32_bf16 v[62:65], v[130:133], v[200:203], v[62:65]
	v_mfma_f32_16x16x32_bf16 v[58:61], v[138:141], v[200:203], v[58:61]
	v_mfma_f32_16x16x32_bf16 v[46:49], v[130:133], v[208:211], v[46:49]
	v_mfma_f32_16x16x32_bf16 v[42:45], v[138:141], v[208:211], v[42:45]
	v_mfma_f32_16x16x32_bf16 v[30:33], v[130:133], v[216:219], v[30:33]
	v_mfma_f32_16x16x32_bf16 v[26:29], v[138:141], v[216:219], v[26:29]
	v_mfma_f32_16x16x32_bf16 v[14:17], v[130:133], v[224:227], v[14:17]
	v_mfma_f32_16x16x32_bf16 v[10:13], v[138:141], v[224:227], v[10:13]
	v_mfma_f32_16x16x32_bf16 v[62:65], v[134:137], v[204:207], v[62:65]
	v_mfma_f32_16x16x32_bf16 v[58:61], v[142:145], v[204:207], v[58:61]
	v_mfma_f32_16x16x32_bf16 v[46:49], v[134:137], v[212:215], v[46:49]
	v_mfma_f32_16x16x32_bf16 v[42:45], v[142:145], v[212:215], v[42:45]
	v_mfma_f32_16x16x32_bf16 v[30:33], v[134:137], v[220:223], v[30:33]
	v_mfma_f32_16x16x32_bf16 v[26:29], v[142:145], v[220:223], v[26:29]
	v_mfma_f32_16x16x32_bf16 v[14:17], v[134:137], v[228:231], v[14:17]
	v_mfma_f32_16x16x32_bf16 v[10:13], v[142:145], v[228:231], v[10:13]
	v_mfma_f32_16x16x32_bf16 v[54:57], v[172:175], v[200:203], v[54:57]
	v_mfma_f32_16x16x32_bf16 v[50:53], v[192:195], v[200:203], v[50:53]
	v_mfma_f32_16x16x32_bf16 v[38:41], v[172:175], v[208:211], v[38:41]
	v_mfma_f32_16x16x32_bf16 v[34:37], v[192:195], v[208:211], v[34:37]
	v_mfma_f32_16x16x32_bf16 v[22:25], v[172:175], v[216:219], v[22:25]
	v_mfma_f32_16x16x32_bf16 v[18:21], v[192:195], v[216:219], v[18:21]
	v_mfma_f32_16x16x32_bf16 v[6:9], v[172:175], v[224:227], v[6:9]
	v_mfma_f32_16x16x32_bf16 v[2:5], v[192:195], v[224:227], v[2:5]
	v_mfma_f32_16x16x32_bf16 v[54:57], v[176:179], v[204:207], v[54:57]
	v_mfma_f32_16x16x32_bf16 v[50:53], v[196:199], v[204:207], v[50:53]
	v_mfma_f32_16x16x32_bf16 v[38:41], v[176:179], v[212:215], v[38:41]
	v_mfma_f32_16x16x32_bf16 v[34:37], v[196:199], v[212:215], v[34:37]
	v_mfma_f32_16x16x32_bf16 v[22:25], v[176:179], v[220:223], v[22:25]
	v_mfma_f32_16x16x32_bf16 v[18:21], v[196:199], v[220:223], v[18:21]
	v_mfma_f32_16x16x32_bf16 v[6:9], v[176:179], v[228:231], v[6:9]
	v_mfma_f32_16x16x32_bf16 v[2:5], v[196:199], v[228:231], v[2:5]
	s_setprio 0
	s_barrier
	s_add_i32 s93, s93, 2
	s_add_u32 s48, s48, 0x100
	s_addc_u32 s49, s49, 0
	s_add_u32 s41, s41, 0x100
	s_addc_u32 s92, s92, 0
	s_cmp_gt_u32 s93, 13
	s_cbranch_scc0 .LBB0_162
	s_add_u32 s94, s34, 0x40080
	s_addc_u32 s95, s5, 0
	v_lshl_add_u64 v[232:233], s[94:95], 0, v[164:165]
	s_add_i32 m0, s47, 0xc000
	v_lshl_add_u64 v[234:235], s[94:95], 0, v[166:167]
	global_load_lds_dwordx4 v[232:233], off
	s_add_i32 m0, s47, 0xe000
	s_nop 0
	global_load_lds_dwordx4 v[234:235], off
	s_and_b64 vcc, exec, s[14:15]
	s_cbranch_vccz .LBB0_165
	s_barrier

; #define PG8_STAGE(bufoff, gbase, voff) do { _Pragma("unroll") for (int _i = 0; _i < 2; ++_i) \
;         __builtin_amdgcn_global_load_lds((const unsigned*)((const char*)(gbase) + (voff)[_i]), (PG8_LAS unsigned*)(lds + (bufoff) + ldsw + _i * 8192), 16, 0, 0); } while (0)
; #define PG8_LDA(dst, b, h) do { _Pragma("unroll") for (int m = 0; m < 4; ++m) _Pragma("unroll") for (int k = 0; k < 2; ++k) dst[m][k] = *(const PG8_LAS bf16x8*)(lds + PG8_SA(b, h) + aoff + m * 2048 + k * 1024); } while (0)
; #define PG8_LDB(dst, b, h) do { _Pragma("unroll") for (int n = 0; n < 2; ++n) _Pragma("unroll") for (int k = 0; k < 2; ++k) dst[n][k] = *(const PG8_LAS bf16x8*)(lds + PG8_SB(b, h) + boff + n * 2048 + k * 1024); } while (0)
; #define PG8_MMA(ai, bj, At, Bt) do { __builtin_amdgcn_s_setprio(1); _Pragma("unroll") for (int m = 0; m < 4; ++m) _Pragma("unroll") for (int n = 0; n < 2; ++n) _Pragma("unroll") for (int k = 0; k < 2; ++k) \
;         acc[ai][bj][m][n] = __builtin_amdgcn_mfma_f32_16x16x32_bf16(Bt[n][k], At[m][k], acc[ai][bj][m][n], 0, 0, 0); __builtin_amdgcn_s_setprio(0); } while (0)
; #define PG8_WAIT_V(n) asm volatile("s_waitcnt vmcnt(" #n ")" ::: "memory")
; #define PG8_WAIT_L(n) asm volatile("s_waitcnt lgkmcnt(" #n ")" ::: "memory")
; #define PG8_BAR __builtin_amdgcn_s_barrier()
; #define PG8_SCHED __builtin_amdgcn_sched_barrier(0)
; template <class Epi, class Sched, bool ALIGN_EPI = false, bool SP2 = false>
; __device__ __forceinline__ void gemm_phase(PG8_LAS unsigned char* lds, const Gemm g, const Sched& S, const Epi& E) {
;     ...
;             PG8_LDB(B0, 0, 0); PG8_LDB(B1, 0, 1); PG8_SCHED; PG8_LDA(At, 0, 0); PG8_STAGE(PG8_SA(1, 1), a1 + hstep, voffA);
;             PG8_WAIT_V(8); PG8_WAIT_L(0); PG8_BAR; PG8_MMA(0, 0, At, B0); PG8_MMA(0, 1, At, B1); PG8_BAR; PG8_SCHED;
;             PG8_LDA(At, 0, 1); PG8_STAGE(PG8_SB(0, 0), b2, voffB); PG8_STAGE(PG8_SB(0, 1), b2 + hstep, voffB); PG8_STAGE(PG8_SA(0, 0), a2, voffA);
;             PG8_WAIT_V(8); PG8_WAIT_L(0); PG8_BAR; PG8_MMA(1, 0, At, B0); PG8_MMA(1, 1, At, B1); PG8_BAR; PG8_SCHED;
;     ...
;         for (int a = 0; a < 2; ++a)
; #pragma unroll
;             for (int b = 0; b < 2; ++b)
; #pragma unroll
;                 for (int m = 0; m < 4; ++m)
; #pragma unroll
;                     for (int n = 0; n < 2; ++n) acc[a][b][m][n] = (f32x4){0.f, 0.f, 0.f, 0.f};
.Lp1_peel:
	ds_read_b128 v[130:133], v183
	ds_read_b128 v[134:137], v183 offset:1024
	ds_read_b128 v[138:141], v183 offset:2048
	ds_read_b128 v[142:145], v183 offset:3072
	ds_read_b128 v[172:175], v184
	ds_read_b128 v[176:179], v184 offset:1024
	ds_read_b128 v[192:195], v184 offset:2048
	ds_read_b128 v[196:199], v184 offset:3072
	s_add_u32 s50, s48, 0xfffc0080
	s_addc_u32 s51, s49, -1
	s_cmp_eq_u32 s93, 12
	s_cselect_b32 s65, s5, s51
	s_cselect_b32 s64, s34, s50
	s_cselect_b32 s51, s27, s92
	s_cselect_b32 s50, s35, s41
	ds_read_b128 v[200:203], v185
	ds_read_b128 v[204:207], v185 offset:1024
	ds_read_b128 v[208:211], v185 offset:2048
	ds_read_b128 v[212:215], v185 offset:3072
	ds_read_b128 v[216:219], v185 offset:4096
	ds_read_b128 v[220:223], v185 offset:5120
	ds_read_b128 v[224:227], v185 offset:6144
	ds_read_b128 v[228:231], v185 offset:7168
	s_waitcnt vmcnt(24)
	s_waitcnt lgkmcnt(0)
	s_setprio 1
	s_barrier
	v_mfma_f32_16x16x32_bf16 v[126:129], v[130:133], v[200:203], 0
	v_mfma_f32_16x16x32_bf16 v[122:125], v[138:141], v[200:203], 0
	v_mfma_f32_16x16x32_bf16 v[110:113], v[130:133], v[208:211], 0
	v_mfma_f32_16x16x32_bf16 v[106:109], v[138:141], v[208:211], 0
	v_mfma_f32_16x16x32_bf16 v[94:97], v[130:133], v[216:219], 0
	v_mfma_f32_16x16x32_bf16 v[90:93], v[138:141], v[216:219], 0
	v_mfma_f32_16x16x32_bf16 v[78:81], v[130:133], v[224:227], 0
	v_mfma_f32_16x16x32_bf16 v[74:77], v[138:141], v[224:227], 0
	v_mfma_f32_16x16x32_bf16 v[126:129], v[134:137], v[204:207], v[126:129]
	v_mfma_f32_16x16x32_bf16 v[122:125], v[142:145], v[204:207], v[122:125]
	v_mfma_f32_16x16x32_bf16 v[110:113], v[134:137], v[212:215], v[110:113]
	v_mfma_f32_16x16x32_bf16 v[106:109], v[142:145], v[212:215], v[106:109]
	v_mfma_f32_16x16x32_bf16 v[94:97], v[134:137], v[220:223], v[94:97]
	v_mfma_f32_16x16x32_bf16 v[90:93], v[142:145], v[220:223], v[90:93]
	v_mfma_f32_16x16x32_bf16 v[78:81], v[134:137], v[228:231], v[78:81]
	v_mfma_f32_16x16x32_bf16 v[74:77], v[142:145], v[228:231], v[74:77]
	v_mfma_f32_16x16x32_bf16 v[118:121], v[172:175], v[200:203], 0
	v_mfma_f32_16x16x32_bf16 v[114:117], v[192:195], v[200:203], 0
	v_mfma_f32_16x16x32_bf16 v[102:105], v[172:175], v[208:211], 0
	v_mfma_f32_16x16x32_bf16 v[98:101], v[192:195], v[208:211], 0
	v_mfma_f32_16x16x32_bf16 v[86:89], v[172:175], v[216:219], 0
	v_mfma_f32_16x16x32_bf16 v[82:85], v[192:195], v[216:219], 0
	v_mfma_f32_16x16x32_bf16 v[70:73], v[172:175], v[224:227], 0
	v_mfma_f32_16x16x32_bf16 v[66:69], v[192:195], v[224:227], 0
	v_mfma_f32_16x16x32_bf16 v[118:121], v[176:179], v[204:207], v[118:121]
	v_mfma_f32_16x16x32_bf16 v[114:117], v[196:199], v[204:207], v[114:117]
	v_mfma_f32_16x16x32_bf16 v[102:105], v[176:179], v[212:215], v[102:105]
	v_mfma_f32_16x16x32_bf16 v[98:101], v[196:199], v[212:215], v[98:101]
	v_mfma_f32_16x16x32_bf16 v[86:89], v[176:179], v[220:223], v[86:89]
	v_mfma_f32_16x16x32_bf16 v[82:85], v[196:199], v[220:223], v[82:85]
	v_mfma_f32_16x16x32_bf16 v[70:73], v[176:179], v[228:231], v[70:73]
	v_mfma_f32_16x16x32_bf16 v[66:69], v[196:199], v[228:231], v[66:69]
	s_setprio 0
	s_barrier
	s_add_i32 s94, s85, s72
	v_lshl_add_u64 v[232:233], s[50:51], 0, v[148:149]
	s_mov_b32 m0, s94
	ds_read_b128 v[200:203], v185 offset:16384
	ds_read_b128 v[204:207], v185 offset:17408
	ds_read_b128 v[208:211], v185 offset:18432
	ds_read_b128 v[212:215], v185 offset:19456
	ds_read_b128 v[216:219], v185 offset:20480
	ds_read_b128 v[220:223], v185 offset:21504
	ds_read_b128 v[224:227], v185 offset:22528
	ds_read_b128 v[228:231], v185 offset:23552
	global_load_lds_dwordx4 v[232:233], off
	s_add_i32 m0, s94, 0x2000
	s_add_u32 s94, s50, 0x40000
	v_lshl_add_u64 v[234:235], s[50:51], 0, v[152:153]
	s_addc_u32 s95, s51, 0
	s_add_i32 s96, s86, s72
	global_load_lds_dwordx4 v[234:235], off
	v_lshl_add_u64 v[236:237], s[94:95], 0, v[148:149]
	s_mov_b32 m0, s96
	v_lshl_add_u64 v[238:239], s[64:65], 0, v[150:151]
	global_load_lds_dwordx4 v[236:237], off
	v_lshl_add_u64 v[236:237], s[94:95], 0, v[152:153]
	s_add_i32 m0, s96, 0x2000
	s_nop 0
	global_load_lds_dwordx4 v[236:237], off
	v_lshl_add_u64 v[236:237], s[64:65], 0, v[146:147]
	s_mov_b32 m0, s47
	s_nop 0
	global_load_lds_dwordx4 v[236:237], off
	s_mov_b32 m0, s73
	s_nop 0
	global_load_lds_dwordx4 v[238:239], off
	s_waitcnt vmcnt(24)
	s_waitcnt lgkmcnt(0)
	s_setprio 1
	s_barrier
	v_mfma_f32_16x16x32_bf16 v[62:65], v[130:133], v[200:203], 0
	v_mfma_f32_16x16x32_bf16 v[58:61], v[138:141], v[200:203], 0
	v_mfma_f32_16x16x32_bf16 v[46:49], v[130:133], v[208:211], 0
	v_mfma_f32_16x16x32_bf16 v[42:45], v[138:141], v[208:211], 0
	v_mfma_f32_16x16x32_bf16 v[30:33], v[130:133], v[216:219], 0
	v_mfma_f32_16x16x32_bf16 v[26:29], v[138:141], v[216:219], 0
	v_mfma_f32_16x16x32_bf16 v[14:17], v[130:133], v[224:227], 0
	v_mfma_f32_16x16x32_bf16 v[10:13], v[138:141], v[224:227], 0
	v_mfma_f32_16x16x32_bf16 v[62:65], v[134:137], v[204:207], v[62:65]
	v_mfma_f32_16x16x32_bf16 v[58:61], v[142:145], v[204:207], v[58:61]
	v_mfma_f32_16x16x32_bf16 v[46:49], v[134:137], v[212:215], v[46:49]
	v_mfma_f32_16x16x32_bf16 v[42:45], v[142:145], v[212:215], v[42:45]
	v_mfma_f32_16x16x32_bf16 v[30:33], v[134:137], v[220:223], v[30:33]
	v_mfma_f32_16x16x32_bf16 v[26:29], v[142:145], v[220:223], v[26:29]
	v_mfma_f32_16x16x32_bf16 v[14:17], v[134:137], v[228:231], v[14:17]
	v_mfma_f32_16x16x32_bf16 v[10:13], v[142:145], v[228:231], v[10:13]
	v_mfma_f32_16x16x32_bf16 v[54:57], v[172:175], v[200:203], 0
	v_mfma_f32_16x16x32_bf16 v[50:53], v[192:195], v[200:203], 0
	v_mfma_f32_16x16x32_bf16 v[38:41], v[172:175], v[208:211], 0
	v_mfma_f32_16x16x32_bf16 v[34:37], v[192:195], v[208:211], 0
	v_mfma_f32_16x16x32_bf16 v[22:25], v[172:175], v[216:219], 0
	v_mfma_f32_16x16x32_bf16 v[18:21], v[192:195], v[216:219], 0
	v_mfma_f32_16x16x32_bf16 v[6:9], v[172:175], v[224:227], 0
	v_mfma_f32_16x16x32_bf16 v[2:5], v[192:195], v[224:227], 0
	v_mfma_f32_16x16x32_bf16 v[54:57], v[176:179], v[204:207], v[54:57]
	v_mfma_f32_16x16x32_bf16 v[50:53], v[196:199], v[204:207], v[50:53]
	v_mfma_f32_16x16x32_bf16 v[38:41], v[176:179], v[212:215], v[38:41]
	v_mfma_f32_16x16x32_bf16 v[34:37], v[196:199], v[212:215], v[34:37]
	v_mfma_f32_16x16x32_bf16 v[22:25], v[176:179], v[220:223], v[22:25]
	v_mfma_f32_16x16x32_bf16 v[18:21], v[196:199], v[220:223], v[18:21]
	v_mfma_f32_16x16x32_bf16 v[6:9], v[176:179], v[228:231], v[6:9]
	v_mfma_f32_16x16x32_bf16 v[2:5], v[196:199], v[228:231], v[2:5]
	s_setprio 0
	s_barrier
; #define PG8_STAGE(bufoff, gbase, voff) do { _Pragma("unroll") for (int _i = 0; _i < 2; ++_i) \
;         __builtin_amdgcn_global_load_lds((const unsigned*)((const char*)(gbase) + (voff)[_i]), (PG8_LAS unsigned*)(lds + (bufoff) + ldsw + _i * 8192), 16, 0, 0); } while (0)
; #define PG8_LDA(dst, b, h) do { _Pragma("unroll") for (int m = 0; m < 4; ++m) _Pragma("unroll") for (int k = 0; k < 2; ++k) dst[m][k] = *(const PG8_LAS bf16x8*)(lds + PG8_SA(b, h) + aoff + m * 2048 + k * 1024); } while (0)
; #define PG8_LDB(dst, b, h) do { _Pragma("unroll") for (int n = 0; n < 2; ++n) _Pragma("unroll") for (int k = 0; k < 2; ++k) dst[n][k] = *(const PG8_LAS bf16x8*)(lds + PG8_SB(b, h) + boff + n * 2048 + k * 1024); } while (0)
; #define PG8_MMA(ai, bj, At, Bt) do { __builtin_amdgcn_s_setprio(1); _Pragma("unroll") for (int m = 0; m < 4; ++m) _Pragma("unroll") for (int n = 0; n < 2; ++n) _Pragma("unroll") for (int k = 0; k < 2; ++k) \
;         acc[ai][bj][m][n] = __builtin_amdgcn_mfma_f32_16x16x32_bf16(Bt[n][k], At[m][k], acc[ai][bj][m][n], 0, 0, 0); __builtin_amdgcn_s_setprio(0); } while (0)
; #define PG8_WAIT_V(n) asm volatile("s_waitcnt vmcnt(" #n ")" ::: "memory")
; #define PG8_WAIT_L(n) asm volatile("s_waitcnt lgkmcnt(" #n ")" ::: "memory")
; #define PG8_BAR __builtin_amdgcn_s_barrier()
; #define PG8_SCHED __builtin_amdgcn_sched_barrier(0)
; template <class Epi, class Sched, bool ALIGN_EPI = false, bool SP2 = false>
; __device__ __forceinline__ void gemm_phase(PG8_LAS unsigned char* lds, const Gemm g, const Sched& S, const Epi& E) {
;     ...
;             PG8_LDB(B0, 1, 0); PG8_LDB(B1, 1, 1); PG8_SCHED; PG8_LDA(At, 1, 0); PG8_STAGE(PG8_SA(0, 1), a2 + hstep, voffA);
;             PG8_WAIT_V(8); PG8_WAIT_L(0); PG8_BAR; PG8_MMA(0, 0, At, B0); PG8_MMA(0, 1, At, B1); PG8_BAR; PG8_SCHED;
;             PG8_LDA(At, 1, 1); PG8_STAGE(PG8_SB(1, 0), b3, voffB); PG8_STAGE(PG8_SB(1, 1), b3 + hstep, voffB); PG8_STAGE(PG8_SA(1, 0), a3, voffA);
;             PG8_WAIT_V(8); PG8_WAIT_L(0); PG8_BAR; PG8_MMA(1, 0, At, B0); PG8_MMA(1, 1, At, B1); PG8_BAR; PG8_SCHED;
	s_add_i32 s94, 0, 0x18000
	s_add_i32 s95, 0, 0x1c000
	v_add_u32_e32 v142, s94, v181
	v_add_u32_e32 v154, s95, v181
	ds_read_b128 v[130:133], v142
	ds_read_b128 v[134:137], v142 offset:1024
	ds_read_b128 v[138:141], v142 offset:2048
	ds_read_b128 v[142:145], v142 offset:3072
	ds_read_b128 v[172:175], v154
	ds_read_b128 v[176:179], v154 offset:1024
	ds_read_b128 v[192:195], v154 offset:2048
	ds_read_b128 v[196:199], v154 offset:3072
	s_add_u32 s64, s64, 0x40000
	s_addc_u32 s65, s65, 0
	s_mov_b32 m0, s74
	v_lshl_add_u64 v[240:241], s[64:65], 0, v[146:147]
	ds_read_b128 v[200:203], v185 offset:32768
	ds_read_b128 v[204:207], v185 offset:33792
	ds_read_b128 v[208:211], v185 offset:34816
	ds_read_b128 v[212:215], v185 offset:35840
	ds_read_b128 v[216:219], v185 offset:36864
	ds_read_b128 v[220:223], v185 offset:37888
	ds_read_b128 v[224:227], v185 offset:38912
	ds_read_b128 v[228:231], v185 offset:39936
	global_load_lds_dwordx4 v[240:241], off
	v_lshl_add_u64 v[240:241], s[64:65], 0, v[150:151]
	s_mov_b32 m0, s75
	s_nop 0
	global_load_lds_dwordx4 v[240:241], off
	s_waitcnt vmcnt(24)
	s_waitcnt lgkmcnt(0)
	s_setprio 1
	s_barrier
	v_mfma_f32_16x16x32_bf16 v[126:129], v[130:133], v[200:203], v[126:129]
	v_mfma_f32_16x16x32_bf16 v[122:125], v[138:141], v[200:203], v[122:125]
	v_mfma_f32_16x16x32_bf16 v[110:113], v[130:133], v[208:211], v[110:113]
	v_mfma_f32_16x16x32_bf16 v[106:109], v[138:141], v[208:211], v[106:109]
	v_mfma_f32_16x16x32_bf16 v[94:97], v[130:133], v[216:219], v[94:97]
	v_mfma_f32_16x16x32_bf16 v[90:93], v[138:141], v[216:219], v[90:93]
	v_mfma_f32_16x16x32_bf16 v[78:81], v[130:133], v[224:227], v[78:81]
	v_mfma_f32_16x16x32_bf16 v[74:77], v[138:141], v[224:227], v[74:77]
	v_mfma_f32_16x16x32_bf16 v[126:129], v[134:137], v[204:207], v[126:129]
	v_mfma_f32_16x16x32_bf16 v[122:125], v[142:145], v[204:207], v[122:125]
	v_mfma_f32_16x16x32_bf16 v[110:113], v[134:137], v[212:215], v[110:113]
	v_mfma_f32_16x16x32_bf16 v[106:109], v[142:145], v[212:215], v[106:109]
	v_mfma_f32_16x16x32_bf16 v[94:97], v[134:137], v[220:223], v[94:97]
	v_mfma_f32_16x16x32_bf16 v[90:93], v[142:145], v[220:223], v[90:93]
	v_mfma_f32_16x16x32_bf16 v[78:81], v[134:137], v[228:231], v[78:81]
	v_mfma_f32_16x16x32_bf16 v[74:77], v[142:145], v[228:231], v[74:77]
	v_mfma_f32_16x16x32_bf16 v[118:121], v[172:175], v[200:203], v[118:121]
	v_mfma_f32_16x16x32_bf16 v[114:117], v[192:195], v[200:203], v[114:117]
	v_mfma_f32_16x16x32_bf16 v[102:105], v[172:175], v[208:211], v[102:105]
	v_mfma_f32_16x16x32_bf16 v[98:101], v[192:195], v[208:211], v[98:101]
	v_mfma_f32_16x16x32_bf16 v[86:89], v[172:175], v[216:219], v[86:89]
	v_mfma_f32_16x16x32_bf16 v[82:85], v[192:195], v[216:219], v[82:85]
	v_mfma_f32_16x16x32_bf16 v[70:73], v[172:175], v[224:227], v[70:73]
	v_mfma_f32_16x16x32_bf16 v[66:69], v[192:195], v[224:227], v[66:69]
	v_mfma_f32_16x16x32_bf16 v[118:121], v[176:179], v[204:207], v[118:121]
	v_mfma_f32_16x16x32_bf16 v[114:117], v[196:199], v[204:207], v[114:117]
	v_mfma_f32_16x16x32_bf16 v[102:105], v[176:179], v[212:215], v[102:105]
	v_mfma_f32_16x16x32_bf16 v[98:101], v[196:199], v[212:215], v[98:101]
	v_mfma_f32_16x16x32_bf16 v[86:89], v[176:179], v[220:223], v[86:89]
	v_mfma_f32_16x16x32_bf16 v[82:85], v[196:199], v[220:223], v[82:85]
	v_mfma_f32_16x16x32_bf16 v[70:73], v[176:179], v[228:231], v[70:73]
	v_mfma_f32_16x16x32_bf16 v[66:69], v[196:199], v[228:231], v[66:69]
	s_setprio 0
	s_barrier
	s_add_i32 s64, s94, s72
	v_lshl_add_u64 v[232:233], v[232:233], 0, s[12:13]
	s_mov_b32 m0, s64
	ds_read_b128 v[200:203], v185 offset:49152
	ds_read_b128 v[204:207], v185 offset:50176
	ds_read_b128 v[208:211], v185 offset:51200
	ds_read_b128 v[212:215], v185 offset:52224
	ds_read_b128 v[216:219], v185 offset:53248
	ds_read_b128 v[220:223], v185 offset:54272
	ds_read_b128 v[224:227], v185 offset:55296
	ds_read_b128 v[228:231], v185 offset:56320
	global_load_lds_dwordx4 v[232:233], off
	s_add_i32 m0, s64, 0x2000
	s_add_u32 s50, s50, 0x40080
	v_lshl_add_u64 v[232:233], v[234:235], 0, s[12:13]
	s_addc_u32 s51, s51, 0
	s_add_i32 s64, s95, s72
	global_load_lds_dwordx4 v[232:233], off
	v_lshl_add_u64 v[232:233], s[50:51], 0, v[148:149]
	s_mov_b32 m0, s64
	s_nop 0
	global_load_lds_dwordx4 v[232:233], off
	v_lshl_add_u64 v[232:233], s[50:51], 0, v[152:153]
	s_add_i32 m0, s64, 0x2000
	s_nop 0
	global_load_lds_dwordx4 v[232:233], off
	v_lshl_add_u64 v[232:233], v[236:237], 0, s[12:13]
	s_mov_b32 m0, s82
	s_nop 0
	global_load_lds_dwordx4 v[232:233], off
	v_lshl_add_u64 v[232:233], v[238:239], 0, s[12:13]
	s_mov_b32 m0, s83
	s_nop 0
	global_load_lds_dwordx4 v[232:233], off
	s_waitcnt vmcnt(8)
	s_waitcnt lgkmcnt(0)
	s_setprio 1
	s_barrier
	v_mfma_f32_16x16x32_bf16 v[62:65], v[130:133], v[200:203], v[62:65]
	v_mfma_f32_16x16x32_bf16 v[58:61], v[138:141], v[200:203], v[58:61]
	v_mfma_f32_16x16x32_bf16 v[46:49], v[130:133], v[208:211], v[46:49]
	v_mfma_f32_16x16x32_bf16 v[42:45], v[138:141], v[208:211], v[42:45]
	v_mfma_f32_16x16x32_bf16 v[30:33], v[130:133], v[216:219], v[30:33]
	v_mfma_f32_16x16x32_bf16 v[26:29], v[138:141], v[216:219], v[26:29]
	v_mfma_f32_16x16x32_bf16 v[14:17], v[130:133], v[224:227], v[14:17]
	v_mfma_f32_16x16x32_bf16 v[10:13], v[138:141], v[224:227], v[10:13]
	v_mfma_f32_16x16x32_bf16 v[62:65], v[134:137], v[204:207], v[62:65]
	v_mfma_f32_16x16x32_bf16 v[58:61], v[142:145], v[204:207], v[58:61]
	v_mfma_f32_16x16x32_bf16 v[46:49], v[134:137], v[212:215], v[46:49]
	v_mfma_f32_16x16x32_bf16 v[42:45], v[142:145], v[212:215], v[42:45]
	v_mfma_f32_16x16x32_bf16 v[30:33], v[134:137], v[220:223], v[30:33]
	v_mfma_f32_16x16x32_bf16 v[26:29], v[142:145], v[220:223], v[26:29]
	v_mfma_f32_16x16x32_bf16 v[14:17], v[134:137], v[228:231], v[14:17]
	v_mfma_f32_16x16x32_bf16 v[10:13], v[142:145], v[228:231], v[10:13]
	v_mfma_f32_16x16x32_bf16 v[54:57], v[172:175], v[200:203], v[54:57]
	v_mfma_f32_16x16x32_bf16 v[50:53], v[192:195], v[200:203], v[50:53]
	v_mfma_f32_16x16x32_bf16 v[38:41], v[172:175], v[208:211], v[38:41]
	v_mfma_f32_16x16x32_bf16 v[34:37], v[192:195], v[208:211], v[34:37]
	v_mfma_f32_16x16x32_bf16 v[22:25], v[172:175], v[216:219], v[22:25]
	v_mfma_f32_16x16x32_bf16 v[18:21], v[192:195], v[216:219], v[18:21]
	v_mfma_f32_16x16x32_bf16 v[6:9], v[172:175], v[224:227], v[6:9]
	v_mfma_f32_16x16x32_bf16 v[2:5], v[192:195], v[224:227], v[2:5]
	v_mfma_f32_16x16x32_bf16 v[54:57], v[176:179], v[204:207], v[54:57]
	v_mfma_f32_16x16x32_bf16 v[50:53], v[196:199], v[204:207], v[50:53]
	v_mfma_f32_16x16x32_bf16 v[38:41], v[176:179], v[212:215], v[38:41]
	v_mfma_f32_16x16x32_bf16 v[34:37], v[196:199], v[212:215], v[34:37]
	v_mfma_f32_16x16x32_bf16 v[22:25], v[176:179], v[220:223], v[22:25]
	v_mfma_f32_16x16x32_bf16 v[18:21], v[196:199], v[220:223], v[18:21]
	v_mfma_f32_16x16x32_bf16 v[6:9], v[176:179], v[228:231], v[6:9]
	v_mfma_f32_16x16x32_bf16 v[2:5], v[196:199], v[228:231], v[2:5]
	s_setprio 0
	s_barrier
	s_add_i32 s93, s93, 2
	s_add_u32 s48, s48, 0x100
	s_addc_u32 s49, s49, 0
	s_add_u32 s41, s41, 0x100
	s_addc_u32 s92, s92, 0
	s_branch .LBB0_162

; #define PG8_STAGE(bufoff, gbase, voff) do { _Pragma("unroll") for (int _i = 0; _i < 2; ++_i) \
;         __builtin_amdgcn_global_load_lds((const unsigned*)((const char*)(gbase) + (voff)[_i]), (PG8_LAS unsigned*)(lds + (bufoff) + ldsw + _i * 8192), 16, 0, 0); } while (0)
; #define PG8_LDA(dst, b, h) do { _Pragma("unroll") for (int m = 0; m < 4; ++m) _Pragma("unroll") for (int k = 0; k < 2; ++k) dst[m][k] = *(const PG8_LAS bf16x8*)(lds + PG8_SA(b, h) + aoff + m * 2048 + k * 1024); } while (0)
; #define PG8_LDB(dst, b, h) do { _Pragma("unroll") for (int n = 0; n < 2; ++n) _Pragma("unroll") for (int k = 0; k < 2; ++k) dst[n][k] = *(const PG8_LAS bf16x8*)(lds + PG8_SB(b, h) + boff + n * 2048 + k * 1024); } while (0)
; #define PG8_MMA(ai, bj, At, Bt) do { __builtin_amdgcn_s_setprio(1); _Pragma("unroll") for (int m = 0; m < 4; ++m) _Pragma("unroll") for (int n = 0; n < 2; ++n) _Pragma("unroll") for (int k = 0; k < 2; ++k) \
;         acc[ai][bj][m][n] = __builtin_amdgcn_mfma_f32_16x16x32_bf16(Bt[n][k], At[m][k], acc[ai][bj][m][n], 0, 0, 0); __builtin_amdgcn_s_setprio(0); } while (0)
; #define PG8_WAIT_V(n) asm volatile("s_waitcnt vmcnt(" #n ")" ::: "memory")
; #define PG8_WAIT_L(n) asm volatile("s_waitcnt lgkmcnt(" #n ")" ::: "memory")
; #define PG8_BAR __builtin_amdgcn_s_barrier()
; #define PG8_SCHED __builtin_amdgcn_sched_barrier(0)
; template <class Epi, class Sched, bool ALIGN_EPI = false, bool SP2 = false>
; __device__ __forceinline__ void gemm_phase(PG8_LAS unsigned char* lds, const Gemm g, const Sched& S, const Epi& E) {
;     ...
;             PG8_LDB(B0, 0, 0); PG8_LDB(B1, 0, 1); PG8_SCHED; PG8_LDA(At, 0, 0); PG8_STAGE(PG8_SA(1, 1), a1 + hstep, voffA);
;             PG8_WAIT_V(8); PG8_WAIT_L(0); PG8_BAR; PG8_MMA(0, 0, At, B0); PG8_MMA(0, 1, At, B1); PG8_BAR; PG8_SCHED;
;             PG8_LDA(At, 0, 1); PG8_STAGE(PG8_SB(0, 0), b2, voffB); PG8_STAGE(PG8_SB(0, 1), b2 + hstep, voffB); PG8_STAGE(PG8_SA(0, 0), a2, voffA);
;             PG8_WAIT_V(8); PG8_WAIT_L(0); PG8_BAR; PG8_MMA(1, 0, At, B0); PG8_MMA(1, 1, At, B1); PG8_BAR; PG8_SCHED;
.LBB0_457:
	ds_read_b128 v[128:131], v169
	ds_read_b128 v[132:135], v169 offset:1024
	ds_read_b128 v[136:139], v169 offset:2048
	ds_read_b128 v[140:143], v169 offset:3072
	ds_read_b128 v[160:163], v170
	ds_read_b128 v[172:175], v170 offset:1024
	ds_read_b128 v[176:179], v170 offset:2048
	ds_read_b128 v[180:183], v170 offset:3072
	s_add_u32 s38, s34, 0xfffc0080
	s_addc_u32 s39, s35, -1
	s_cmp_eq_u32 s65, 12
	s_cselect_b32 s41, s25, s39
	s_cselect_b32 s40, s61, s38
	s_cselect_b32 s39, s21, s64
	s_cselect_b32 s38, s62, s63
	v_lshl_add_u64 v[164:165], s[34:35], 0, v[152:153]
	s_add_i32 m0, s31, 0xc000
	ds_read_b128 v[184:187], v171
	ds_read_b128 v[188:191], v171 offset:1024
	ds_read_b128 v[192:195], v171 offset:2048
	ds_read_b128 v[196:199], v171 offset:3072
	ds_read_b128 v[200:203], v171 offset:4096
	ds_read_b128 v[204:207], v171 offset:5120
	ds_read_b128 v[208:211], v171 offset:6144
	ds_read_b128 v[212:215], v171 offset:7168
	global_load_lds_dwordx4 v[164:165], off
	v_lshl_add_u64 v[164:165], s[34:35], 0, v[154:155]
	s_add_i32 m0, s31, 0xe000
	s_nop 0
	global_load_lds_dwordx4 v[164:165], off
	s_waitcnt vmcnt(8)
	s_waitcnt lgkmcnt(0)
	s_setprio 1
	s_barrier
	v_mfma_f32_16x16x32_bf16 v[124:127], v[128:131], v[184:187], v[124:127]
	v_mfma_f32_16x16x32_bf16 v[120:123], v[136:139], v[184:187], v[120:123]
	v_mfma_f32_16x16x32_bf16 v[116:119], v[128:131], v[192:195], v[116:119]
	v_mfma_f32_16x16x32_bf16 v[112:115], v[136:139], v[192:195], v[112:115]
	v_mfma_f32_16x16x32_bf16 v[96:99], v[128:131], v[200:203], v[96:99]
	v_mfma_f32_16x16x32_bf16 v[88:91], v[136:139], v[200:203], v[88:91]
	v_mfma_f32_16x16x32_bf16 v[84:87], v[128:131], v[208:211], v[84:87]
	v_mfma_f32_16x16x32_bf16 v[76:79], v[136:139], v[208:211], v[76:79]
	v_mfma_f32_16x16x32_bf16 v[124:127], v[132:135], v[188:191], v[124:127]
	v_mfma_f32_16x16x32_bf16 v[120:123], v[140:143], v[188:191], v[120:123]
	v_mfma_f32_16x16x32_bf16 v[116:119], v[132:135], v[196:199], v[116:119]
	v_mfma_f32_16x16x32_bf16 v[112:115], v[140:143], v[196:199], v[112:115]
	v_mfma_f32_16x16x32_bf16 v[96:99], v[132:135], v[204:207], v[96:99]
	v_mfma_f32_16x16x32_bf16 v[88:91], v[140:143], v[204:207], v[88:91]
	v_mfma_f32_16x16x32_bf16 v[84:87], v[132:135], v[212:215], v[84:87]
	v_mfma_f32_16x16x32_bf16 v[76:79], v[140:143], v[212:215], v[76:79]
	v_mfma_f32_16x16x32_bf16 v[108:111], v[160:163], v[184:187], v[108:111]
	v_mfma_f32_16x16x32_bf16 v[104:107], v[176:179], v[184:187], v[104:107]
	v_mfma_f32_16x16x32_bf16 v[100:103], v[160:163], v[192:195], v[100:103]
	v_mfma_f32_16x16x32_bf16 v[92:95], v[176:179], v[192:195], v[92:95]
	v_mfma_f32_16x16x32_bf16 v[80:83], v[160:163], v[200:203], v[80:83]
	v_mfma_f32_16x16x32_bf16 v[72:75], v[176:179], v[200:203], v[72:75]
	v_mfma_f32_16x16x32_bf16 v[68:71], v[160:163], v[208:211], v[68:71]
	v_mfma_f32_16x16x32_bf16 v[64:67], v[176:179], v[208:211], v[64:67]
	v_mfma_f32_16x16x32_bf16 v[108:111], v[172:175], v[188:191], v[108:111]
	v_mfma_f32_16x16x32_bf16 v[104:107], v[180:183], v[188:191], v[104:107]
	v_mfma_f32_16x16x32_bf16 v[100:103], v[172:175], v[196:199], v[100:103]
	v_mfma_f32_16x16x32_bf16 v[92:95], v[180:183], v[196:199], v[92:95]
	v_mfma_f32_16x16x32_bf16 v[80:83], v[172:175], v[204:207], v[80:83]
	v_mfma_f32_16x16x32_bf16 v[72:75], v[180:183], v[204:207], v[72:75]
	v_mfma_f32_16x16x32_bf16 v[68:71], v[172:175], v[212:215], v[68:71]
	v_mfma_f32_16x16x32_bf16 v[64:67], v[180:183], v[212:215], v[64:67]
	s_setprio 0
	s_barrier
	s_add_i32 s68, s58, s45
	v_lshl_add_u64 v[164:165], s[38:39], 0, v[146:147]
	s_mov_b32 m0, s68
	ds_read_b128 v[184:187], v171 offset:16384
	ds_read_b128 v[188:191], v171 offset:17408
	ds_read_b128 v[192:195], v171 offset:18432
	ds_read_b128 v[196:199], v171 offset:19456
	ds_read_b128 v[200:203], v171 offset:20480
	ds_read_b128 v[204:207], v171 offset:21504
	ds_read_b128 v[208:211], v171 offset:22528
	ds_read_b128 v[212:215], v171 offset:23552
	global_load_lds_dwordx4 v[164:165], off
	s_add_i32 m0, s68, 0x2000
	s_add_u32 s68, s38, 0x40000
	v_lshl_add_u64 v[216:217], s[38:39], 0, v[150:151]
	s_addc_u32 s69, s39, 0
	s_add_i32 s70, s59, s45
	global_load_lds_dwordx4 v[216:217], off
	v_lshl_add_u64 v[218:219], s[68:69], 0, v[146:147]
	s_mov_b32 m0, s70
	v_lshl_add_u64 v[220:221], s[40:41], 0, v[148:149]
	global_load_lds_dwordx4 v[218:219], off
	v_lshl_add_u64 v[218:219], s[68:69], 0, v[150:151]
	s_add_i32 m0, s70, 0x2000
	s_nop 0
	global_load_lds_dwordx4 v[218:219], off
	v_lshl_add_u64 v[218:219], s[40:41], 0, v[144:145]
	s_mov_b32 m0, s31
	s_nop 0
	global_load_lds_dwordx4 v[218:219], off
	s_mov_b32 m0, s48
	s_nop 0
	global_load_lds_dwordx4 v[220:221], off
	s_waitcnt vmcnt(8)
	s_waitcnt lgkmcnt(0)
	s_setprio 1
	s_barrier
; #define PG8_STAGE(bufoff, gbase, voff) do { _Pragma("unroll") for (int _i = 0; _i < 2; ++_i) \
;         __builtin_amdgcn_global_load_lds((const unsigned*)((const char*)(gbase) + (voff)[_i]), (PG8_LAS unsigned*)(lds + (bufoff) + ldsw + _i * 8192), 16, 0, 0); } while (0)
; #define PG8_LDA(dst, b, h) do { _Pragma("unroll") for (int m = 0; m < 4; ++m) _Pragma("unroll") for (int k = 0; k < 2; ++k) dst[m][k] = *(const PG8_LAS bf16x8*)(lds + PG8_SA(b, h) + aoff + m * 2048 + k * 1024); } while (0)
; #define PG8_LDB(dst, b, h) do { _Pragma("unroll") for (int n = 0; n < 2; ++n) _Pragma("unroll") for (int k = 0; k < 2; ++k) dst[n][k] = *(const PG8_LAS bf16x8*)(lds + PG8_SB(b, h) + boff + n * 2048 + k * 1024); } while (0)
; #define PG8_MMA(ai, bj, At, Bt) do { __builtin_amdgcn_s_setprio(1); _Pragma("unroll") for (int m = 0; m < 4; ++m) _Pragma("unroll") for (int n = 0; n < 2; ++n) _Pragma("unroll") for (int k = 0; k < 2; ++k) \
;         acc[ai][bj][m][n] = __builtin_amdgcn_mfma_f32_16x16x32_bf16(Bt[n][k], At[m][k], acc[ai][bj][m][n], 0, 0, 0); __builtin_amdgcn_s_setprio(0); } while (0)
; #define PG8_WAIT_V(n) asm volatile("s_waitcnt vmcnt(" #n ")" ::: "memory")
; #define PG8_WAIT_L(n) asm volatile("s_waitcnt lgkmcnt(" #n ")" ::: "memory")
; #define PG8_BAR __builtin_amdgcn_s_barrier()
; #define PG8_SCHED __builtin_amdgcn_sched_barrier(0)
; template <class Epi, class Sched, bool ALIGN_EPI = false, bool SP2 = false>
; __device__ __forceinline__ void gemm_phase(PG8_LAS unsigned char* lds, const Gemm g, const Sched& S, const Epi& E) {
;     ...
;             PG8_WAIT_V(8); PG8_WAIT_L(0); PG8_BAR; PG8_MMA(1, 0, At, B0); PG8_MMA(1, 1, At, B1); PG8_BAR; PG8_SCHED;
;             PG8_LDB(B0, 1, 0); PG8_LDB(B1, 1, 1); PG8_SCHED; PG8_LDA(At, 1, 0); PG8_STAGE(PG8_SA(0, 1), a2 + hstep, voffA);
;             PG8_WAIT_V(8); PG8_WAIT_L(0); PG8_BAR; PG8_MMA(0, 0, At, B0); PG8_MMA(0, 1, At, B1); PG8_BAR; PG8_SCHED;
	v_mfma_f32_16x16x32_bf16 v[60:63], v[128:131], v[184:187], v[60:63]
	v_mfma_f32_16x16x32_bf16 v[56:59], v[136:139], v[184:187], v[56:59]
	v_mfma_f32_16x16x32_bf16 v[52:55], v[128:131], v[192:195], v[52:55]
	v_mfma_f32_16x16x32_bf16 v[48:51], v[136:139], v[192:195], v[48:51]
	v_mfma_f32_16x16x32_bf16 v[36:39], v[128:131], v[200:203], v[36:39]
	v_mfma_f32_16x16x32_bf16 v[24:27], v[136:139], v[200:203], v[24:27]
	v_mfma_f32_16x16x32_bf16 v[20:23], v[128:131], v[208:211], v[20:23]
	v_mfma_f32_16x16x32_bf16 v[12:15], v[136:139], v[208:211], v[12:15]
	v_mfma_f32_16x16x32_bf16 v[60:63], v[132:135], v[188:191], v[60:63]
	v_mfma_f32_16x16x32_bf16 v[56:59], v[140:143], v[188:191], v[56:59]
	v_mfma_f32_16x16x32_bf16 v[52:55], v[132:135], v[196:199], v[52:55]
	v_mfma_f32_16x16x32_bf16 v[48:51], v[140:143], v[196:199], v[48:51]
	v_mfma_f32_16x16x32_bf16 v[36:39], v[132:135], v[204:207], v[36:39]
	v_mfma_f32_16x16x32_bf16 v[24:27], v[140:143], v[204:207], v[24:27]
	v_mfma_f32_16x16x32_bf16 v[20:23], v[132:135], v[212:215], v[20:23]
	v_mfma_f32_16x16x32_bf16 v[12:15], v[140:143], v[212:215], v[12:15]
	v_mfma_f32_16x16x32_bf16 v[44:47], v[160:163], v[184:187], v[44:47]
	v_mfma_f32_16x16x32_bf16 v[40:43], v[176:179], v[184:187], v[40:43]
	v_mfma_f32_16x16x32_bf16 v[32:35], v[160:163], v[192:195], v[32:35]
	v_mfma_f32_16x16x32_bf16 v[28:31], v[176:179], v[192:195], v[28:31]
	v_mfma_f32_16x16x32_bf16 v[16:19], v[160:163], v[200:203], v[16:19]
	v_mfma_f32_16x16x32_bf16 v[8:11], v[176:179], v[200:203], v[8:11]
	v_mfma_f32_16x16x32_bf16 v[4:7], v[160:163], v[208:211], v[4:7]
	v_mfma_f32_16x16x32_bf16 v[0:3], v[176:179], v[208:211], v[0:3]
	v_mfma_f32_16x16x32_bf16 v[44:47], v[172:175], v[188:191], v[44:47]
	v_mfma_f32_16x16x32_bf16 v[40:43], v[180:183], v[188:191], v[40:43]
	v_mfma_f32_16x16x32_bf16 v[32:35], v[172:175], v[196:199], v[32:35]
	v_mfma_f32_16x16x32_bf16 v[28:31], v[180:183], v[196:199], v[28:31]
	v_mfma_f32_16x16x32_bf16 v[16:19], v[172:175], v[204:207], v[16:19]
	v_mfma_f32_16x16x32_bf16 v[8:11], v[180:183], v[204:207], v[8:11]
	v_mfma_f32_16x16x32_bf16 v[4:7], v[172:175], v[212:215], v[4:7]
	v_mfma_f32_16x16x32_bf16 v[0:3], v[180:183], v[212:215], v[0:3]
	s_setprio 0
	s_barrier
	s_add_i32 s68, 0, 0x18000
	s_add_i32 s69, 0, 0x1c000
	v_add_u32_e32 v140, s68, v167
	v_add_u32_e32 v180, s69, v167
	ds_read_b128 v[128:131], v140
	ds_read_b128 v[132:135], v140 offset:1024
	ds_read_b128 v[136:139], v140 offset:2048
	ds_read_b128 v[140:143], v140 offset:3072
	ds_read_b128 v[160:163], v180
	ds_read_b128 v[172:175], v180 offset:1024
	ds_read_b128 v[176:179], v180 offset:2048
	ds_read_b128 v[180:183], v180 offset:3072
	s_add_u32 s40, s40, 0x40000
	s_addc_u32 s41, s41, 0
	s_mov_b32 m0, s49
	v_lshl_add_u64 v[222:223], s[40:41], 0, v[144:145]
	ds_read_b128 v[184:187], v171 offset:32768
	ds_read_b128 v[188:191], v171 offset:33792
	ds_read_b128 v[192:195], v171 offset:34816
	ds_read_b128 v[196:199], v171 offset:35840
	ds_read_b128 v[200:203], v171 offset:36864
	ds_read_b128 v[204:207], v171 offset:37888
	ds_read_b128 v[208:211], v171 offset:38912
	ds_read_b128 v[212:215], v171 offset:39936
	global_load_lds_dwordx4 v[222:223], off
	v_lshl_add_u64 v[222:223], s[40:41], 0, v[148:149]
	s_mov_b32 m0, s50
	s_nop 0
	global_load_lds_dwordx4 v[222:223], off
	s_waitcnt vmcnt(8)
	s_waitcnt lgkmcnt(0)
	s_setprio 1
	s_barrier
	v_mfma_f32_16x16x32_bf16 v[124:127], v[128:131], v[184:187], v[124:127]
	v_mfma_f32_16x16x32_bf16 v[120:123], v[136:139], v[184:187], v[120:123]
	v_mfma_f32_16x16x32_bf16 v[116:119], v[128:131], v[192:195], v[116:119]
	v_mfma_f32_16x16x32_bf16 v[112:115], v[136:139], v[192:195], v[112:115]
	v_mfma_f32_16x16x32_bf16 v[96:99], v[128:131], v[200:203], v[96:99]
	v_mfma_f32_16x16x32_bf16 v[88:91], v[136:139], v[200:203], v[88:91]
	v_mfma_f32_16x16x32_bf16 v[84:87], v[128:131], v[208:211], v[84:87]
	v_mfma_f32_16x16x32_bf16 v[76:79], v[136:139], v[208:211], v[76:79]
	v_mfma_f32_16x16x32_bf16 v[124:127], v[132:135], v[188:191], v[124:127]
	v_mfma_f32_16x16x32_bf16 v[120:123], v[140:143], v[188:191], v[120:123]
	v_mfma_f32_16x16x32_bf16 v[116:119], v[132:135], v[196:199], v[116:119]
	v_mfma_f32_16x16x32_bf16 v[112:115], v[140:143], v[196:199], v[112:115]
	v_mfma_f32_16x16x32_bf16 v[96:99], v[132:135], v[204:207], v[96:99]
	v_mfma_f32_16x16x32_bf16 v[88:91], v[140:143], v[204:207], v[88:91]
	v_mfma_f32_16x16x32_bf16 v[84:87], v[132:135], v[212:215], v[84:87]
	v_mfma_f32_16x16x32_bf16 v[76:79], v[140:143], v[212:215], v[76:79]
	v_mfma_f32_16x16x32_bf16 v[108:111], v[160:163], v[184:187], v[108:111]
	v_mfma_f32_16x16x32_bf16 v[104:107], v[176:179], v[184:187], v[104:107]
	v_mfma_f32_16x16x32_bf16 v[100:103], v[160:163], v[192:195], v[100:103]
	v_mfma_f32_16x16x32_bf16 v[92:95], v[176:179], v[192:195], v[92:95]
	v_mfma_f32_16x16x32_bf16 v[80:83], v[160:163], v[200:203], v[80:83]
	v_mfma_f32_16x16x32_bf16 v[72:75], v[176:179], v[200:203], v[72:75]
	v_mfma_f32_16x16x32_bf16 v[68:71], v[160:163], v[208:211], v[68:71]
	v_mfma_f32_16x16x32_bf16 v[64:67], v[176:179], v[208:211], v[64:67]
	v_mfma_f32_16x16x32_bf16 v[108:111], v[172:175], v[188:191], v[108:111]
	v_mfma_f32_16x16x32_bf16 v[104:107], v[180:183], v[188:191], v[104:107]
	v_mfma_f32_16x16x32_bf16 v[100:103], v[172:175], v[196:199], v[100:103]
	v_mfma_f32_16x16x32_bf16 v[92:95], v[180:183], v[196:199], v[92:95]
	v_mfma_f32_16x16x32_bf16 v[80:83], v[172:175], v[204:207], v[80:83]
	v_mfma_f32_16x16x32_bf16 v[72:75], v[180:183], v[204:207], v[72:75]
	v_mfma_f32_16x16x32_bf16 v[68:71], v[172:175], v[212:215], v[68:71]
	v_mfma_f32_16x16x32_bf16 v[64:67], v[180:183], v[212:215], v[64:67]
	s_setprio 0
	s_barrier
; #define PG8_STAGE(bufoff, gbase, voff) do { _Pragma("unroll") for (int _i = 0; _i < 2; ++_i) \
;         __builtin_amdgcn_global_load_lds((const unsigned*)((const char*)(gbase) + (voff)[_i]), (PG8_LAS unsigned*)(lds + (bufoff) + ldsw + _i * 8192), 16, 0, 0); } while (0)
; #define PG8_LDA(dst, b, h) do { _Pragma("unroll") for (int m = 0; m < 4; ++m) _Pragma("unroll") for (int k = 0; k < 2; ++k) dst[m][k] = *(const PG8_LAS bf16x8*)(lds + PG8_SA(b, h) + aoff + m * 2048 + k * 1024); } while (0)
; #define PG8_MMA(ai, bj, At, Bt) do { __builtin_amdgcn_s_setprio(1); _Pragma("unroll") for (int m = 0; m < 4; ++m) _Pragma("unroll") for (int n = 0; n < 2; ++n) _Pragma("unroll") for (int k = 0; k < 2; ++k) \
;         acc[ai][bj][m][n] = __builtin_amdgcn_mfma_f32_16x16x32_bf16(Bt[n][k], At[m][k], acc[ai][bj][m][n], 0, 0, 0); __builtin_amdgcn_s_setprio(0); } while (0)
; #define PG8_WAIT_V(n) asm volatile("s_waitcnt vmcnt(" #n ")" ::: "memory")
; #define PG8_WAIT_L(n) asm volatile("s_waitcnt lgkmcnt(" #n ")" ::: "memory")
; #define PG8_BAR __builtin_amdgcn_s_barrier()
; #define PG8_SCHED __builtin_amdgcn_sched_barrier(0)
; template <class Epi, class Sched, bool ALIGN_EPI = false, bool SP2 = false>
; __device__ __forceinline__ void gemm_phase(PG8_LAS unsigned char* lds, const Gemm g, const Sched& S, const Epi& E) {
;     ...
;             PG8_LDA(At, 1, 1); PG8_STAGE(PG8_SB(1, 0), b3, voffB); PG8_STAGE(PG8_SB(1, 1), b3 + hstep, voffB); PG8_STAGE(PG8_SA(1, 0), a3, voffA);
;             PG8_WAIT_V(8); PG8_WAIT_L(0); PG8_BAR; PG8_MMA(1, 0, At, B0); PG8_MMA(1, 1, At, B1); PG8_BAR; PG8_SCHED;
	s_add_i32 s40, s68, s45
	v_lshl_add_u64 v[164:165], v[164:165], 0, s[6:7]
	s_mov_b32 m0, s40
	ds_read_b128 v[184:187], v171 offset:49152
	ds_read_b128 v[188:191], v171 offset:50176
	ds_read_b128 v[192:195], v171 offset:51200
	ds_read_b128 v[196:199], v171 offset:52224
	ds_read_b128 v[200:203], v171 offset:53248
	ds_read_b128 v[204:207], v171 offset:54272
	ds_read_b128 v[208:211], v171 offset:55296
	ds_read_b128 v[212:215], v171 offset:56320
	global_load_lds_dwordx4 v[164:165], off
	s_add_i32 m0, s40, 0x2000
	s_add_u32 s38, s38, 0x40080
	v_lshl_add_u64 v[164:165], v[216:217], 0, s[6:7]
	s_addc_u32 s39, s39, 0
	s_add_i32 s40, s69, s45
	global_load_lds_dwordx4 v[164:165], off
	v_lshl_add_u64 v[164:165], s[38:39], 0, v[146:147]
	s_mov_b32 m0, s40
	s_nop 0
	global_load_lds_dwordx4 v[164:165], off
	v_lshl_add_u64 v[164:165], s[38:39], 0, v[150:151]
	s_add_i32 m0, s40, 0x2000
	s_nop 0
	global_load_lds_dwordx4 v[164:165], off
	v_lshl_add_u64 v[164:165], v[218:219], 0, s[6:7]
	s_mov_b32 m0, s56
	s_nop 0
	global_load_lds_dwordx4 v[164:165], off
	v_lshl_add_u64 v[164:165], v[220:221], 0, s[6:7]
	s_mov_b32 m0, s57
	s_nop 0
	global_load_lds_dwordx4 v[164:165], off
	s_waitcnt vmcnt(8)
	s_waitcnt lgkmcnt(0)
	s_setprio 1
	s_barrier
	v_mfma_f32_16x16x32_bf16 v[60:63], v[128:131], v[184:187], v[60:63]
	v_mfma_f32_16x16x32_bf16 v[56:59], v[136:139], v[184:187], v[56:59]
	v_mfma_f32_16x16x32_bf16 v[52:55], v[128:131], v[192:195], v[52:55]
	v_mfma_f32_16x16x32_bf16 v[48:51], v[136:139], v[192:195], v[48:51]
	v_mfma_f32_16x16x32_bf16 v[36:39], v[128:131], v[200:203], v[36:39]
	v_mfma_f32_16x16x32_bf16 v[24:27], v[136:139], v[200:203], v[24:27]
	v_mfma_f32_16x16x32_bf16 v[20:23], v[128:131], v[208:211], v[20:23]
	v_mfma_f32_16x16x32_bf16 v[12:15], v[136:139], v[208:211], v[12:15]
	v_mfma_f32_16x16x32_bf16 v[60:63], v[132:135], v[188:191], v[60:63]
	v_mfma_f32_16x16x32_bf16 v[56:59], v[140:143], v[188:191], v[56:59]
	v_mfma_f32_16x16x32_bf16 v[52:55], v[132:135], v[196:199], v[52:55]
	v_mfma_f32_16x16x32_bf16 v[48:51], v[140:143], v[196:199], v[48:51]
	v_mfma_f32_16x16x32_bf16 v[36:39], v[132:135], v[204:207], v[36:39]
	v_mfma_f32_16x16x32_bf16 v[24:27], v[140:143], v[204:207], v[24:27]
	v_mfma_f32_16x16x32_bf16 v[20:23], v[132:135], v[212:215], v[20:23]
	v_mfma_f32_16x16x32_bf16 v[12:15], v[140:143], v[212:215], v[12:15]
	v_mfma_f32_16x16x32_bf16 v[44:47], v[160:163], v[184:187], v[44:47]
	v_mfma_f32_16x16x32_bf16 v[40:43], v[176:179], v[184:187], v[40:43]
	v_mfma_f32_16x16x32_bf16 v[32:35], v[160:163], v[192:195], v[32:35]
	v_mfma_f32_16x16x32_bf16 v[28:31], v[176:179], v[192:195], v[28:31]
	v_mfma_f32_16x16x32_bf16 v[16:19], v[160:163], v[200:203], v[16:19]
	v_mfma_f32_16x16x32_bf16 v[8:11], v[176:179], v[200:203], v[8:11]
	v_mfma_f32_16x16x32_bf16 v[4:7], v[160:163], v[208:211], v[4:7]
	v_mfma_f32_16x16x32_bf16 v[0:3], v[176:179], v[208:211], v[0:3]
	v_mfma_f32_16x16x32_bf16 v[44:47], v[172:175], v[188:191], v[44:47]
	v_mfma_f32_16x16x32_bf16 v[40:43], v[180:183], v[188:191], v[40:43]
	v_mfma_f32_16x16x32_bf16 v[32:35], v[172:175], v[196:199], v[32:35]
	v_mfma_f32_16x16x32_bf16 v[28:31], v[180:183], v[196:199], v[28:31]
	v_mfma_f32_16x16x32_bf16 v[16:19], v[172:175], v[204:207], v[16:19]
	v_mfma_f32_16x16x32_bf16 v[8:11], v[180:183], v[204:207], v[8:11]
	v_mfma_f32_16x16x32_bf16 v[4:7], v[172:175], v[212:215], v[4:7]
	v_mfma_f32_16x16x32_bf16 v[0:3], v[180:183], v[212:215], v[0:3]
	s_setprio 0
	s_barrier
	s_add_i32 s65, s65, 2
	s_add_u32 s34, s34, 0x100
	s_addc_u32 s35, s35, 0
	s_add_u32 s63, s63, 0x100
	s_addc_u32 s64, s64, 0
	s_cmp_gt_u32 s65, 13
	s_cbranch_scc0 .LBB0_457
	s_and_b64 vcc, exec, s[8:9]
	s_cbranch_vccz .LBB0_460
	s_barrier
